# baseline (speedup 1.0000x reference)
.LBB0_296:
	s_or_b64 exec, exec, s[0:1]
	s_add_u32 s0, s60, 0xbe00000
	s_addc_u32 s1, s61, 0
	v_writelane_b32 v252, s0, 36
	s_cmpk_lt_i32 s62, 0x80
	s_waitcnt lgkmcnt(0)
	v_writelane_b32 v252, s1, 37
	s_cselect_b64 s[0:1], -1, 0
	s_cmp_lt_i32 s70, 64
	s_cselect_b64 s[4:5], -1, 0
	s_or_b64 s[2:3], s[4:5], s[0:1]
	s_and_b64 vcc, exec, s[2:3]
	s_barrier
	s_cbranch_vccz .LBB0_321
	v_mov_b32_e32 v144, v218
	s_andn2_b64 vcc, exec, s[4:5]
	v_readfirstlane_b32 s19, v144
	s_cbranch_vccnz .LBB0_321
	s_and_b32 s98, s70, 7
	s_lshr_b32 s99, s70, 3
	s_lshl_b32 s99, s99, 2
	s_and_b32 s100, s98, 4
	s_lshl_b32 s100, s100, 3
	s_or_b32 s99, s99, s100
	s_and_b32 s98, s98, 3
	s_or_b32 s99, s99, s98
	s_lshr_b32 s98, s99, 3
	s_and_b32 s99, s99, 7
	s_lshl_b32 s99, s99, 3
	s_add_i32 s99, s99, s98
	s_ashr_i32 s2, s99, 31
	s_lshr_b32 s2, s2, 29
	s_add_i32 s2, s99, s2
	s_and_b32 s3, s2, -8
	s_sub_i32 s6, s99, s3
	s_cmp_gt_i32 s6, -1
	s_cbranch_scc0 .LBB0_300
	s_lshl_b32 s3, s6, 3
	s_cbranch_execz .LBB0_301
	s_branch .LBB0_302
